# code placement: 60 B pad before out-proj region, 36 B before in-proj region (unreachable s_nop), on top of v13
# speedup vs baseline: 1.0000x; 1.0000x over previous
.LBB0_307:
	s_waitcnt vmcnt(8) lgkmcnt(0)
	s_barrier
	v_mov_b32_e32 v241, 0x3ecc95a3
	s_setprio 0
	s_and_b64 vcc, exec, s[42:43]
	s_cbranch_vccz .LBB0_293
	s_branch .LBB0_294
	s_nop 0
	s_nop 0
	s_nop 0
	s_nop 0
	s_nop 0
	s_nop 0
	s_nop 0
	s_nop 0
	s_nop 0
	s_nop 0
	s_nop 0
	s_nop 0
	s_nop 0
	s_nop 0
	s_nop 0

.LBB0_450:
	s_andn2_b64 vcc, exec, s[16:17]
	s_cbranch_vccnz .LBB0_339
	s_barrier
	s_branch .LBB0_339
	s_nop 0
	s_nop 0
	s_nop 0
	s_nop 0
	s_nop 0
	s_nop 0
	s_nop 0
	s_nop 0
	s_nop 0
